# prenorm token loops (both instances): gain/scale/shift quarter rows loaded together, next token row prefetched during the current token
# speedup vs baseline: 1.0751x; 1.0059x over previous
; __device__ __forceinline__ int ltid(int wvs) { int t = (wvs << 6) | (int)__builtin_amdgcn_mbcnt_hi(~0u, __builtin_amdgcn_mbcnt_lo(~0u, 0u)); asm volatile("" : "+v"(t)); return t; }
; __device__ __forceinline__ int lbid() { int b = __builtin_amdgcn_workgroup_id_x(); asm volatile("" : "+s"(b)); return b; }
; __device__ __forceinline__ void phase_prenorm(const int wvs, const Params& p, int layer, int which  , const float* lat, const float* ctx, bool fold) {
;   const int lane = ltid(wvs) & 63, gw = lbid() * 8 + (ltid(wvs) >> 6);
;   const float* gain = p.in[which == 0 ? I_NMIX : I_NMLP] + layer * DM; const float* mods = (const float*)(p.ws + OFF_MODS) + (size_t)layer * 5 * 6144;
;   hf* A = (hf*)(p.ws + OFF_AY);
; #pragma unroll 2
;   for (int tok = gw; tok < NTOK; tok += NWAVES) {
;     bool isctx; const size_t ro = xrow_off(tok, isctx); const float* xr = (isctx ? ctx : lat) + ro; const int mi = mod_index(tok);
;     const float* sh = mods + (size_t)mi * 6144 + (which == 0 ? 0 : 3) * DM; const float* sc = sh + DM;
;     f32x4 v[4]; float ss = 0.f;
; #pragma unroll
;     for (int i = 0; i < 4; ++i) v[i] = *(const f32x4*)(xr + lane * 4 + 256 * i);
;     if (fold && isctx) {
;       const float* gt = (const float*)(p.ws + OFF_MODS) + (size_t)4 * 6144 + (which == 1 ? 2 : 5) * DM;
;       const float* part = (const float*)(p.ws + OFF_RI) + ro; float* xc = (float*)(p.ws + OFF_XCTX) + ro;
; #pragma unroll
;       for (int i = 0; i < 4; ++i) { const int k = lane * 4 + 256 * i; f32x4 s = *(const f32x4*)(part + k);
; #pragma unroll
;         for (int q = 1; q < 4; ++q) s += *(const f32x4*)(part + (size_t)q * (NB * LCTX * DM) + k);
;         v[i] += *(const f32x4*)(gt + k) * s; *(f32x4*)(xc + k) = v[i]; } }
; #pragma unroll
;     for (int i = 0; i < 4; ++i) ss += v[i][0] * v[i][0] + v[i][1] * v[i][1] + v[i][2] * v[i][2] + v[i][3] * v[i][3];
;     ss = wave_sum(ss); const float rs = rsqrtf(ss * (1.0f / DM) + 1e-6f);
; #pragma unroll
;     for (int i = 0; i < 4; ++i) { const int k = lane * 4 + 256 * i; const f32x4 g4 = *(const f32x4*)(gain + k), s4 = *(const f32x4*)(sc + k), h4v = *(const f32x4*)(sh + k); h4 o;
.LBB0_522:
	s_mov_b64 s[10:11], s[0:1]
	v_mov_b32_e32 v4, v193
	s_mov_b32 s2, s28
	v_mov_b32_e32 v0, v193
	v_readlane_b32 s3, v254, 9
	s_lshl_b32 s16, s2, 3
	s_waitcnt lgkmcnt(0)
	s_lshl_b32 s4, s3, 10
	v_ashrrev_i32_e32 v2, 6, v0
	s_mov_b32 s5, s31
	v_add_u32_e32 v19, s16, v2
	v_writelane_b32 v254, s4, 14
	s_movk_i32 s2, 0x4400
	v_cmp_gt_i32_e32 vcc, s2, v19
	v_writelane_b32 v254, s5, 15
	s_mul_i32 s2, s3, 0x7800
	v_writelane_b32 v254, s2, 16
	s_nop 1
	v_writelane_b32 v254, s3, 17
	s_and_saveexec_b64 s[8:9], vcc
	s_cbranch_execz .LBB0_533
	s_load_dwordx4 s[4:7], s[10:11], 0x130
	s_load_dwordx2 s[2:3], s[10:11], 0x0
	s_load_dwordx2 s[12:13], s[10:11], 0x10
	s_load_dwordx2 s[14:15], s[10:11], 0x30
	s_and_b64 s[10:11], s[38:39], exec
	v_lshlrev_b32_e32 v0, 2, v4
	s_waitcnt lgkmcnt(0)
	s_cselect_b32 s11, s3, s5
	s_cselect_b32 s10, s2, s4
	s_add_u32 s2, s6, 0x270c000
	s_addc_u32 s3, s7, 0
	s_and_b64 s[4:5], s[38:39], exec
	v_readlane_b32 s4, v254, 14
	v_readlane_b32 s5, v254, 15
	s_cselect_b32 s13, s13, s3
	s_cselect_b32 s12, s12, s2
	s_lshl_b64 s[4:5], s[4:5], 2
	s_add_u32 s4, s14, s4
	s_addc_u32 s5, s15, s5
	v_readlane_b32 s14, v254, 16
	v_readlane_b32 s15, v254, 17
	s_mov_b32 s15, s31
	s_mov_b32 s18, s14
	s_lshl_b64 s[14:15], s[14:15], 2
	s_add_u32 s14, s6, s14
	s_addc_u32 s15, s7, s15
	s_add_u32 s14, s14, 0x26d0000
	v_and_b32_e32 v18, 0xfc, v0
	s_addc_u32 s15, s15, 0
	v_lshlrev_b32_e32 v0, 2, v18
	v_or_b32_e32 v6, 0x100, v18
	v_lshl_add_u64 v[20:21], s[4:5], 0, v[0:1]
	s_add_u32 s4, s6, 0x26ed000
	v_or_b32_e32 v8, 0x200, v18
	s_addc_u32 s5, s7, 0
	v_lshlrev_b32_e32 v12, 2, v6
	v_mov_b32_e32 v13, v1
	v_or_b32_e32 v10, 0x300, v18
	v_lshl_add_u64 v[24:25], s[4:5], 0, v[12:13]
	v_lshlrev_b32_e32 v12, 2, v8
	v_ashrrev_i32_e32 v3, 31, v2
	s_ashr_i32 s17, s16, 31
	v_lshl_add_u64 v[26:27], s[4:5], 0, v[12:13]
	v_lshlrev_b32_e32 v12, 2, v10
	v_lshl_add_u64 v[2:3], v[2:3], 0, s[16:17]
	v_lshl_add_u64 v[22:23], s[4:5], 0, v[0:1]
	v_lshl_add_u64 v[28:29], s[4:5], 0, v[12:13]
	v_lshl_add_u64 v[12:13], s[6:7], 0, v[0:1]
	v_lshl_add_u64 v[32:33], s[2:3], 0, v[0:1]
	v_lshlrev_b64 v[2:3], 11, v[2:3]
	v_and_b32_e32 v0, 63, v4
	v_lshl_or_b32 v2, v0, 3, v2
	s_mov_b64 s[4:5], 0xc40c000
	v_lshl_add_u64 v[2:3], s[6:7], 0, v[2:3]
	s_mov_b64 s[2:3], 0x2b0c400
	v_writelane_b32 v254, s18, 16
	v_lshl_add_u64 v[30:31], v[12:13], 0, s[4:5]
	v_lshl_add_u64 v[34:35], v[2:3], 0, s[2:3]
	s_mov_b64 s[6:7], 0
	v_lshlrev_b32_e32 v36, 2, v6
	v_lshlrev_b32_e32 v38, 2, v8
	v_lshlrev_b32_e32 v40, 2, v10
	v_writelane_b32 v254, s19, 17
	v_mov_b32_e32 v150, v19
	v_mul_hi_i32 v151, v150, s89
	v_lshrrev_b32_e32 v152, 31, v151
	v_ashrrev_i32_e32 v151, 11, v151
	v_add_u32_e32 v151, v151, v152
	v_mad_i32_i24 v152, v151, s82, v150
	v_lshlrev_b32_e32 v153, 12, v151
	v_add3_u32 v153, v152, v153, s62
	v_lshl_add_u32 v154, v151, 8, v152
	v_cmp_gt_i32_e32 vcc, s33, v152
	v_mov_b32_e32 v156, s10
	v_mov_b32_e32 v157, s11
	v_mov_b32_e32 v158, s12
	v_mov_b32_e32 v159, s13
	v_cndmask_b32_e32 v154, v153, v154, vcc
	v_cndmask_b32_e32 v156, v156, v158, vcc
	v_cndmask_b32_e32 v157, v157, v159, vcc
	v_ashrrev_i32_e32 v155, 31, v154
	v_lshlrev_b64 v[154:155], 12, v[154:155]
	v_lshl_add_u64 v[154:155], v[156:157], 0, v[154:155]
	v_lshlrev_b32_e32 v152, 2, v18
	v_mov_b32_e32 v153, 0
	v_lshl_add_u64 v[154:155], v[154:155], 0, v[152:153]
	global_load_dwordx4 v[160:163], v[154:155], off
	global_load_dwordx4 v[164:167], v[154:155], off offset:1024
	global_load_dwordx4 v[168:171], v[154:155], off offset:2048
	global_load_dwordx4 v[172:175], v[154:155], off offset:3072
	s_waitcnt vmcnt(0)
	s_branch .LBB0_525
.LBB0_524:
	s_or_b64 exec, exec, s[4:5]
	v_lshl_add_u64 v[50:51], s[14:15], 0, v[42:43]
	v_lshl_add_u64 v[54:55], v[50:51], 0, s[40:41]
	v_lshl_add_u64 v[46:47], v[54:55], 0, v[0:1]
	global_load_dwordx4 v[42:45], v[20:21], off
	v_lshl_add_u64 v[56:57], v[50:51], 0, v[0:1]
	v_mov_b64_e32 v[148:149], v[46:47]
	global_load_dwordx4 v[46:49], v[46:47], off
	v_pk_mul_f32 v[70:71], v[14:15], v[14:15]
	global_load_dwordx4 v[50:53], v[56:57], off
	v_pk_mul_f32 v[72:73], v[10:11], v[10:11]
	global_load_dwordx4 v[100:103], v[20:21], off offset:1024
	global_load_dwordx4 v[104:107], v[148:149], off offset:1024
	global_load_dwordx4 v[108:111], v[56:57], off offset:1024
	global_load_dwordx4 v[112:115], v[20:21], off offset:2048
	global_load_dwordx4 v[116:119], v[148:149], off offset:2048
	global_load_dwordx4 v[120:123], v[56:57], off offset:2048
	global_load_dwordx4 v[124:127], v[20:21], off offset:3072
	global_load_dwordx4 v[128:131], v[148:149], off offset:3072
	global_load_dwordx4 v[132:135], v[56:57], off offset:3072
	v_add_u32_e32 v150, 0x800, v19
	v_min_i32_e32 v150, 0x43ff, v150
	v_mul_hi_i32 v151, v150, s89
	v_lshrrev_b32_e32 v152, 31, v151
	v_ashrrev_i32_e32 v151, 11, v151
	v_add_u32_e32 v151, v151, v152
	v_mad_i32_i24 v152, v151, s82, v150
	v_lshlrev_b32_e32 v153, 12, v151
	v_add3_u32 v153, v152, v153, s62
	v_lshl_add_u32 v154, v151, 8, v152
	v_cmp_gt_i32_e32 vcc, s33, v152
	v_mov_b32_e32 v156, s10
	v_mov_b32_e32 v157, s11
	v_mov_b32_e32 v158, s12
	v_mov_b32_e32 v159, s13
	v_cndmask_b32_e32 v154, v153, v154, vcc
	v_cndmask_b32_e32 v156, v156, v158, vcc
	v_cndmask_b32_e32 v157, v157, v159, vcc
	v_ashrrev_i32_e32 v155, 31, v154
	v_lshlrev_b64 v[154:155], 12, v[154:155]
	v_lshl_add_u64 v[154:155], v[156:157], 0, v[154:155]
	v_lshlrev_b32_e32 v152, 2, v18
	v_mov_b32_e32 v153, 0
	v_lshl_add_u64 v[154:155], v[154:155], 0, v[152:153]
	global_load_dwordx4 v[160:163], v[154:155], off
	global_load_dwordx4 v[164:167], v[154:155], off offset:1024
	global_load_dwordx4 v[168:171], v[154:155], off offset:2048
; __device__ __forceinline__ void phase_prenorm(const int wvs, const Params& p, int layer, int which  , const float* lat, const float* ctx, bool fold) {
;     ...
; #pragma unroll
;     for (int i = 0; i < 4; ++i) ss += v[i][0] * v[i][0] + v[i][1] * v[i][1] + v[i][2] * v[i][2] + v[i][3] * v[i][3];
;     ss = wave_sum(ss); const float rs = rsqrtf(ss * (1.0f / DM) + 1e-6f);
; #pragma unroll
;     for (int i = 0; i < 4; ++i) { const int k = lane * 4 + 256 * i; const f32x4 g4 = *(const f32x4*)(gain + k), s4 = *(const f32x4*)(sc + k), h4v = *(const f32x4*)(sh + k); h4 o;
; #pragma unroll
;       for (int j = 0; j < 4; ++j) o[j] = (hf)((v[i][j] * rs * g4[j]) * (1.0f + s4[j]) + h4v[j]);
;       *(h4*)(A + (size_t)tok * DM + k) = o; }
	global_load_dwordx4 v[172:175], v[154:155], off offset:3072
	v_pk_mul_f32 v[58:59], v[4:5], v[4:5]
	v_pk_mul_f32 v[60:61], v[8:9], v[8:9]
	v_pk_mul_f32 v[62:63], v[2:3], v[2:3]
	v_pk_mul_f32 v[64:65], v[6:7], v[6:7]
	v_pk_mul_f32 v[66:67], v[16:17], v[16:17]
	v_pk_mul_f32 v[68:69], v[12:13], v[12:13]
	v_mov_b32_e32 v74, v70
	v_mov_b32_e32 v75, v72
	v_mov_b32_e32 v72, v71
	v_mov_b32_e32 v70, v66
	v_mov_b32_e32 v71, v68
	v_mov_b32_e32 v68, v67
	v_mov_b32_e32 v66, v62
	v_mov_b32_e32 v67, v64
	v_mov_b32_e32 v64, v63
	v_mov_b32_e32 v62, v58
	v_mov_b32_e32 v63, v60
	v_mov_b32_e32 v60, v59
	v_pk_add_f32 v[58:59], v[74:75], v[72:73]
	v_pk_add_f32 v[64:65], v[66:67], v[64:65]
	v_pk_add_f32 v[58:59], v[70:71], v[58:59]
	v_pk_add_f32 v[62:63], v[62:63], v[64:65]
	v_pk_add_f32 v[58:59], v[68:69], v[58:59]
	v_pk_add_f32 v[60:61], v[60:61], v[62:63]
	v_add_f32_e32 v0, v58, v59
	v_add_f32_e32 v0, v61, v0
	v_add_f32_e32 v0, v60, v0
	v_mov_b32_e32 v39, v1
	v_mov_b32_e32 v41, v1
	v_add_f32_dpp v0, v0, v0 quad_perm:[1,0,3,2] row_mask:0xf bank_mask:0xf bound_ctrl:1
	s_nop 1
	v_add_f32_dpp v0, v0, v0 quad_perm:[2,3,0,1] row_mask:0xf bank_mask:0xf bound_ctrl:1
	s_nop 1
	v_add_f32_dpp v0, v0, v0 row_half_mirror row_mask:0xf bank_mask:0xf bound_ctrl:1
	s_nop 1
	v_add_f32_dpp v0, v0, v0 row_mirror row_mask:0xf bank_mask:0xf bound_ctrl:1
	s_nop 0
	v_readlane_b32 s4, v0, 16
	v_readlane_b32 s5, v0, 48
	v_readlane_b32 s2, v0, 0
	v_readlane_b32 s3, v0, 32
	v_mov_b32_e32 v58, s4
	v_mov_b32_e32 v59, s5
	v_pk_add_f32 v[58:59], s[2:3], v[58:59]
	s_mov_b64 s[2:3], 0x400000
	v_add_f32_e32 v0, v58, v59
	v_fmamk_f32 v0, v0, 0x3a800000, v205
	v_mul_f32_e32 v37, 0x4b800000, v0
	v_cmp_gt_f32_e32 vcc, s34, v0
	s_nop 1
	v_cndmask_b32_e32 v0, v0, v37, vcc
	v_rsq_f32_e32 v0, v0
	v_mov_b32_e32 v37, v1
	v_lshl_add_u64 v[58:59], v[54:55], 0, v[36:37]
	v_mul_f32_e32 v37, 0x45800000, v0
	v_cndmask_b32_e32 v0, v0, v37, vcc
	v_pk_mul_f32 v[14:15], v[14:15], v[0:1] op_sel_hi:[1,0]
	v_pk_mul_f32 v[16:17], v[16:17], v[0:1] op_sel_hi:[1,0]
	v_pk_mul_f32 v[10:11], v[10:11], v[0:1] op_sel_hi:[1,0]
	v_pk_mul_f32 v[12:13], v[12:13], v[0:1] op_sel_hi:[1,0]
	v_pk_mul_f32 v[6:7], v[6:7], v[0:1] op_sel_hi:[1,0]
	v_pk_mul_f32 v[8:9], v[8:9], v[0:1] op_sel_hi:[1,0]
	v_pk_mul_f32 v[2:3], v[2:3], v[0:1] op_sel_hi:[1,0]
	v_pk_mul_f32 v[4:5], v[4:5], v[0:1] op_sel_hi:[1,0]
	v_add_u32_e32 v37, 0x800, v19
	v_cmp_lt_i32_e32 vcc, s83, v19
	s_or_b64 s[6:7], vcc, s[6:7]
	v_mov_b32_e32 v19, v37
	s_waitcnt vmcnt(15)
	v_pk_mul_f32 v[14:15], v[42:43], v[14:15]
	v_pk_mul_f32 v[16:17], v[44:45], v[16:17]
	s_waitcnt vmcnt(14)
	v_pk_add_f32 v[42:43], v[46:47], 1.0 op_sel_hi:[1,0]
	v_pk_add_f32 v[44:45], v[48:49], 1.0 op_sel_hi:[1,0]
	s_waitcnt vmcnt(13)
	v_pk_fma_f32 v[14:15], v[42:43], v[14:15], v[50:51]
	v_pk_fma_f32 v[16:17], v[44:45], v[16:17], v[52:53]
	v_cvt_pk_f16_f32 v14, v14, v15
	v_cvt_pk_f16_f32 v15, v16, v17
	global_store_dwordx2 v[34:35], v[14:15], off offset:-1024
	s_waitcnt vmcnt(5)
	v_mov_b64_e32 v[14:15], v[100:101]
	v_mov_b64_e32 v[16:17], v[102:103]
	s_nop 0
	v_mov_b64_e32 v[42:43], v[104:105]
	v_mov_b64_e32 v[44:45], v[106:107]
	v_mov_b64_e32 v[46:47], v[108:109]
	v_mov_b64_e32 v[48:49], v[110:111]
	v_lshl_add_u64 v[50:51], v[54:55], 0, v[38:39]
	v_pk_mul_f32 v[10:11], v[14:15], v[10:11]
	v_pk_add_f32 v[14:15], v[42:43], 1.0 op_sel_hi:[1,0]
	v_pk_mul_f32 v[12:13], v[16:17], v[12:13]
	v_pk_add_f32 v[16:17], v[44:45], 1.0 op_sel_hi:[1,0]
	v_pk_fma_f32 v[10:11], v[14:15], v[10:11], v[46:47]
	v_pk_fma_f32 v[12:13], v[16:17], v[12:13], v[48:49]
	v_cvt_pk_f16_f32 v10, v10, v11
	v_cvt_pk_f16_f32 v11, v12, v13
	global_store_dwordx2 v[34:35], v[10:11], off offset:-512
	v_mov_b64_e32 v[10:11], v[112:113]
	v_mov_b64_e32 v[12:13], v[114:115]
	s_nop 0
	v_mov_b64_e32 v[14:15], v[116:117]
	v_mov_b64_e32 v[16:17], v[118:119]
	v_mov_b64_e32 v[42:43], v[120:121]
	v_mov_b64_e32 v[44:45], v[122:123]
	v_lshl_add_u64 v[46:47], v[54:55], 0, v[40:41]
	v_pk_mul_f32 v[6:7], v[10:11], v[6:7]
	v_pk_add_f32 v[10:11], v[14:15], 1.0 op_sel_hi:[1,0]
	v_pk_mul_f32 v[8:9], v[12:13], v[8:9]
	v_pk_add_f32 v[12:13], v[16:17], 1.0 op_sel_hi:[1,0]
	v_pk_fma_f32 v[6:7], v[10:11], v[6:7], v[42:43]
	v_pk_fma_f32 v[8:9], v[12:13], v[8:9], v[44:45]
	v_cvt_pk_f16_f32 v6, v6, v7
	v_cvt_pk_f16_f32 v7, v8, v9
	global_store_dwordx2 v[34:35], v[6:7], off
	v_mov_b64_e32 v[6:7], v[124:125]
	v_mov_b64_e32 v[8:9], v[126:127]
	s_nop 0
	v_mov_b64_e32 v[10:11], v[128:129]
	v_mov_b64_e32 v[12:13], v[130:131]
	v_mov_b64_e32 v[14:15], v[132:133]
	v_mov_b64_e32 v[16:17], v[134:135]
	v_pk_mul_f32 v[2:3], v[2:3], v[6:7]
	v_pk_add_f32 v[6:7], v[10:11], 1.0 op_sel_hi:[1,0]
	v_pk_mul_f32 v[4:5], v[4:5], v[8:9]
	v_pk_add_f32 v[8:9], v[12:13], 1.0 op_sel_hi:[1,0]
	v_pk_fma_f32 v[2:3], v[2:3], v[6:7], v[14:15]
	v_pk_fma_f32 v[4:5], v[4:5], v[8:9], v[16:17]
	v_cvt_pk_f16_f32 v2, v2, v3
	v_cvt_pk_f16_f32 v3, v4, v5
	global_store_dwordx2 v[34:35], v[2:3], off offset:512
	v_lshl_add_u64 v[34:35], v[34:35], 0, s[2:3]
	s_andn2_b64 exec, exec, s[6:7]
	s_cbranch_execz .LBB0_533
; __device__ __forceinline__ void phase_prenorm(const int wvs, const Params& p, int layer, int which  , const float* lat, const float* ctx, bool fold) {
;     ...
;   for (int tok = gw; tok < NTOK; tok += NWAVES) {
;     bool isctx; const size_t ro = xrow_off(tok, isctx); const float* xr = (isctx ? ctx : lat) + ro; const int mi = mod_index(tok);
;     const float* sh = mods + (size_t)mi * 6144 + (which == 0 ? 0 : 3) * DM; const float* sc = sh + DM;
;     f32x4 v[4]; float ss = 0.f;
; #pragma unroll
;     for (int i = 0; i < 4; ++i) v[i] = *(const f32x4*)(xr + lane * 4 + 256 * i);
;     if (fold && isctx) {
;       const float* gt = (const float*)(p.ws + OFF_MODS) + (size_t)4 * 6144 + (which == 1 ? 2 : 5) * DM;
;       const float* part = (const float*)(p.ws + OFF_RI) + ro; float* xc = (float*)(p.ws + OFF_XCTX) + ro;
; #pragma unroll
;       for (int i = 0; i < 4; ++i) { const int k = lane * 4 + 256 * i; f32x4 s = *(const f32x4*)(part + k);
; #pragma unroll
;         for (int q = 1; q < 4; ++q) s += *(const f32x4*)(part + (size_t)q * (NB * LCTX * DM) + k);
;         v[i] += *(const f32x4*)(gt + k) * s; *(f32x4*)(xc + k) = v[i]; } }
.LBB0_525:
	v_mul_hi_i32 v0, v19, s89
	v_lshrrev_b32_e32 v2, 31, v0
	v_ashrrev_i32_e32 v0, 11, v0
	v_add_u32_e32 v0, v0, v2
	v_mad_i32_i24 v4, v0, s82, v19
	v_cmp_gt_i32_e32 vcc, s33, v4
	v_cmp_lt_i32_e64 s[4:5], s29, v4
	s_and_saveexec_b64 s[2:3], s[4:5]
	s_xor_b64 s[4:5], exec, s[2:3]
	v_lshlrev_b32_e32 v2, 12, v0
	v_add3_u32 v44, v4, v2, s62
	v_mul_hi_i32_i24_e32 v43, 0x6000, v0
	v_mul_i32_i24_e32 v42, 0x6000, v0
	s_or_saveexec_b64 s[4:5], s[4:5]
	v_mov_b64_e32 v[2:3], s[10:11]
	s_xor_b64 exec, exec, s[4:5]
	v_lshl_add_u32 v44, v0, 8, v4
	v_mov_b64_e32 v[42:43], 0x18000
	v_mov_b64_e32 v[2:3], s[12:13]
	s_or_b64 exec, exec, s[4:5]
	v_ashrrev_i32_e32 v45, 31, v44
	v_lshlrev_b64 v[4:5], 12, v[44:45]
	v_lshl_add_u64 v[2:3], v[2:3], 0, v[4:5]
	v_lshlrev_b32_e32 v0, 2, v18
	v_lshl_add_u64 v[2:3], v[2:3], 0, v[0:1]
	s_waitcnt vmcnt(4)
	v_mov_b64_e32 v[14:15], v[160:161]
	v_mov_b64_e32 v[16:17], v[162:163]
	v_mov_b64_e32 v[10:11], v[164:165]
	v_mov_b64_e32 v[12:13], v[166:167]
	v_mov_b64_e32 v[6:7], v[168:169]
	v_mov_b64_e32 v[8:9], v[170:171]
	v_mov_b64_e32 v[2:3], v[172:173]
	v_mov_b64_e32 v[4:5], v[174:175]
	s_and_b64 s[2:3], s[96:97], vcc
	s_xor_b64 s[2:3], s[2:3], -1
	s_and_saveexec_b64 s[4:5], s[2:3]
	s_xor_b64 s[4:5], exec, s[4:5]
	s_andn2_saveexec_b64 s[4:5], s[4:5]
	s_cbranch_execz .LBB0_524
	v_lshlrev_b64 v[44:45], 10, v[44:45]
	v_lshlrev_b64 v[80:81], 2, v[44:45]
	v_lshl_add_u64 v[82:83], v[30:31], 0, v[80:81]
	v_add_co_u32_e32 v72, vcc, 0x400000, v82
	v_lshl_add_u64 v[80:81], v[32:33], 0, v[80:81]
	s_nop 0
	v_addc_co_u32_e32 v73, vcc, 0, v83, vcc
	global_load_dwordx4 v[44:47], v[72:73], off
	global_load_dwordx4 v[48:51], v[82:83], off
	global_load_dwordx4 v[52:55], v[82:83], off offset:1024
	global_load_dwordx4 v[56:59], v[72:73], off offset:1024
	global_load_dwordx4 v[60:63], v[72:73], off offset:2048
	global_load_dwordx4 v[64:67], v[82:83], off offset:2048
	global_load_dwordx4 v[68:71], v[82:83], off offset:3072
	v_add_co_u32_e32 v84, vcc, 0x800000, v82
	global_load_dwordx4 v[72:75], v[72:73], off offset:3072
	s_nop 0
	v_addc_co_u32_e32 v85, vcc, 0, v83, vcc
	v_add_co_u32_e32 v82, vcc, 0xc00000, v82
	global_load_dwordx4 v[76:79], v[84:85], off
	s_nop 0
	v_addc_co_u32_e32 v83, vcc, 0, v83, vcc
	s_waitcnt vmcnt(7)
	v_pk_add_f32 v[86:87], v[50:51], v[46:47]
	v_pk_add_f32 v[88:89], v[48:49], v[44:45]
	global_load_dwordx4 v[44:47], v[84:85], off offset:1024
	global_load_dwordx4 v[48:51], v[84:85], off offset:2048
	s_waitcnt vmcnt(7)
	v_pk_add_f32 v[90:91], v[54:55], v[58:59]
	v_pk_add_f32 v[92:93], v[52:53], v[56:57]
	global_load_dwordx4 v[52:55], v[84:85], off offset:3072
	global_load_dwordx4 v[56:59], v[82:83], off
	s_waitcnt vmcnt(7)
	v_pk_add_f32 v[84:85], v[66:67], v[62:63]
	v_pk_add_f32 v[94:95], v[64:65], v[60:61]
	s_waitcnt vmcnt(5)
	v_pk_add_f32 v[74:75], v[70:71], v[74:75]
	v_pk_add_f32 v[72:73], v[68:69], v[72:73]
	global_load_dwordx4 v[60:63], v[82:83], off offset:1024
	global_load_dwordx4 v[64:67], v[82:83], off offset:2048
	global_load_dwordx4 v[68:71], v[82:83], off offset:3072
	s_waitcnt vmcnt(7)
	v_pk_add_f32 v[78:79], v[86:87], v[78:79]
	v_pk_add_f32 v[76:77], v[88:89], v[76:77]
	s_waitcnt vmcnt(6)
	v_pk_add_f32 v[82:83], v[90:91], v[46:47]
	v_pk_add_f32 v[86:87], v[92:93], v[44:45]
	s_waitcnt vmcnt(5)
	v_pk_add_f32 v[84:85], v[84:85], v[50:51]
	v_pk_add_f32 v[88:89], v[94:95], v[48:49]
	global_load_dwordx4 v[44:47], v[22:23], off
	global_load_dwordx4 v[48:51], v[24:25], off
	s_waitcnt vmcnt(6)
	v_pk_add_f32 v[74:75], v[74:75], v[54:55]
	v_pk_add_f32 v[72:73], v[72:73], v[52:53]
	global_load_dwordx4 v[52:55], v[26:27], off
	s_waitcnt vmcnt(6)
	v_pk_add_f32 v[78:79], v[78:79], v[58:59]
	v_pk_add_f32 v[76:77], v[76:77], v[56:57]
	global_load_dwordx4 v[56:59], v[28:29], off
	s_waitcnt vmcnt(6)
	v_pk_add_f32 v[62:63], v[82:83], v[62:63]
	v_pk_add_f32 v[60:61], v[86:87], v[60:61]
	s_waitcnt vmcnt(5)
	v_pk_add_f32 v[66:67], v[84:85], v[66:67]
	v_pk_add_f32 v[64:65], v[88:89], v[64:65]
	s_waitcnt vmcnt(4)
	v_pk_add_f32 v[70:71], v[74:75], v[70:71]
	v_pk_add_f32 v[68:69], v[72:73], v[68:69]
	s_waitcnt vmcnt(3)
	v_pk_fma_f32 v[16:17], v[78:79], v[46:47], v[16:17]
	v_pk_fma_f32 v[14:15], v[76:77], v[44:45], v[14:15]
	s_waitcnt vmcnt(2)
	v_pk_fma_f32 v[12:13], v[62:63], v[50:51], v[12:13]
	v_pk_fma_f32 v[10:11], v[60:61], v[48:49], v[10:11]
	s_waitcnt vmcnt(1)
	v_pk_fma_f32 v[8:9], v[66:67], v[54:55], v[8:9]
	v_pk_fma_f32 v[6:7], v[64:65], v[52:53], v[6:7]
	s_waitcnt vmcnt(0)
	v_pk_fma_f32 v[4:5], v[70:71], v[58:59], v[4:5]
	v_pk_fma_f32 v[2:3], v[68:69], v[56:57], v[2:3]
	global_store_dwordx4 v[80:81], v[14:17], off
	global_store_dwordx4 v[80:81], v[10:13], off offset:1024
	global_store_dwordx4 v[80:81], v[6:9], off offset:2048
	global_store_dwordx4 v[80:81], v[2:5], off offset:3072
	s_branch .LBB0_524

; __device__ __forceinline__ void phase_prenorm(const int wvs, const Params& p, int layer, int which  , const float* lat, const float* ctx, bool fold) {
;     ...
;   for (int tok = gw; tok < NTOK; tok += NWAVES) {
;     bool isctx; const size_t ro = xrow_off(tok, isctx); const float* xr = (isctx ? ctx : lat) + ro; const int mi = mod_index(tok);
;     const float* sh = mods + (size_t)mi * 6144 + (which == 0 ? 0 : 3) * DM; const float* sc = sh + DM;
;     f32x4 v[4]; float ss = 0.f;
; #pragma unroll
;     for (int i = 0; i < 4; ++i) v[i] = *(const f32x4*)(xr + lane * 4 + 256 * i);
;     if (fold && isctx) {
;       const float* gt = (const float*)(p.ws + OFF_MODS) + (size_t)4 * 6144 + (which == 1 ? 2 : 5) * DM;
;       const float* part = (const float*)(p.ws + OFF_RI) + ro; float* xc = (float*)(p.ws + OFF_XCTX) + ro;
; #pragma unroll
;       for (int i = 0; i < 4; ++i) { const int k = lane * 4 + 256 * i; f32x4 s = *(const f32x4*)(part + k);
; #pragma unroll
;         for (int q = 1; q < 4; ++q) s += *(const f32x4*)(part + (size_t)q * (NB * LCTX * DM) + k);
;         v[i] += *(const f32x4*)(gt + k) * s; *(f32x4*)(xc + k) = v[i]; } }
; #pragma unroll
;     for (int i = 0; i < 4; ++i) ss += v[i][0] * v[i][0] + v[i][1] * v[i][1] + v[i][2] * v[i][2] + v[i][3] * v[i][3];
;     ss = wave_sum(ss); const float rs = rsqrtf(ss * (1.0f / DM) + 1e-6f);
; #pragma unroll
;     for (int i = 0; i < 4; ++i) { const int k = lane * 4 + 256 * i; const f32x4 g4 = *(const f32x4*)(gain + k), s4 = *(const f32x4*)(sc + k), h4v = *(const f32x4*)(sh + k); h4 o;
.LBB0_1727:
	s_mov_b64 s[14:15], s[0:1]
	v_mov_b32_e32 v4, v193
	s_mov_b32 s2, s28
	v_mov_b32_e32 v0, v193
	s_lshl_b32 s6, s2, 3
	s_movk_i32 s2, 0x4400
	v_ashrrev_i32_e32 v2, 6, v0
	v_add_u32_e32 v19, s6, v2
	v_cmp_gt_i32_e32 vcc, s2, v19
	s_waitcnt lgkmcnt(0)
	s_and_saveexec_b64 s[12:13], vcc
	s_cbranch_execz .LBB0_1738
	s_load_dwordx4 s[8:11], s[14:15], 0x130
	s_load_dwordx2 s[2:3], s[14:15], 0x10
	s_load_dwordx2 s[4:5], s[14:15], 0x38
	v_lshlrev_b32_e32 v0, 2, v4
	v_and_b32_e32 v18, 0xfc, v0
	s_waitcnt lgkmcnt(0)
	s_add_u32 s18, s10, 0x270c000
	s_addc_u32 s19, s11, 0
	s_and_b64 s[14:15], s[38:39], exec
	s_cselect_b32 s15, s3, s19
	s_cselect_b32 s14, s2, s18
	v_readlane_b32 s2, v254, 14
	v_readlane_b32 s3, v254, 15
	s_lshl_b64 s[2:3], s[2:3], 2
	s_add_u32 s2, s4, s2
	s_addc_u32 s3, s5, s3
	v_readlane_b32 s4, v254, 16
	v_readlane_b32 s5, v254, 17
	s_mov_b32 s5, s31
	s_lshl_b64 s[4:5], s[4:5], 2
	s_add_u32 s4, s10, s4
	s_addc_u32 s5, s11, s5
	s_add_u32 s16, s4, 0x26d3000
	s_addc_u32 s17, s5, 0
	v_lshlrev_b32_e32 v0, 2, v18
	v_or_b32_e32 v6, 0x100, v18
	v_lshl_add_u64 v[20:21], s[2:3], 0, v[0:1]
	s_add_u32 s2, s10, 0x26ea000
	v_or_b32_e32 v8, 0x200, v18
	s_addc_u32 s3, s11, 0
	v_lshlrev_b32_e32 v12, 2, v6
	v_mov_b32_e32 v13, v1
	v_or_b32_e32 v10, 0x300, v18
	v_lshl_add_u64 v[24:25], s[2:3], 0, v[12:13]
	v_lshlrev_b32_e32 v12, 2, v8
	v_ashrrev_i32_e32 v3, 31, v2
	s_ashr_i32 s7, s6, 31
	v_lshl_add_u64 v[26:27], s[2:3], 0, v[12:13]
	v_lshlrev_b32_e32 v12, 2, v10
	v_lshl_add_u64 v[2:3], v[2:3], 0, s[6:7]
	v_lshl_add_u64 v[22:23], s[2:3], 0, v[0:1]
	v_lshl_add_u64 v[28:29], s[2:3], 0, v[12:13]
	v_lshl_add_u64 v[12:13], s[10:11], 0, v[0:1]
	v_lshl_add_u64 v[32:33], s[18:19], 0, v[0:1]
	v_lshlrev_b64 v[2:3], 11, v[2:3]
	v_and_b32_e32 v0, 63, v4
	s_mov_b64 s[2:3], 0xc40c000
	v_lshl_or_b32 v2, v0, 3, v2
	v_lshl_add_u64 v[30:31], v[12:13], 0, s[2:3]
	v_lshl_add_u64 v[2:3], s[10:11], 0, v[2:3]
	s_mov_b64 s[2:3], 0x2b0c400
	v_lshl_add_u64 v[34:35], v[2:3], 0, s[2:3]
	s_mov_b64 s[10:11], 0
	v_lshlrev_b32_e32 v36, 2, v6
	v_lshlrev_b32_e32 v38, 2, v8
	v_lshlrev_b32_e32 v40, 2, v10
	v_mov_b32_e32 v150, v19
	v_mul_hi_i32 v151, v150, s89
	v_lshrrev_b32_e32 v152, 31, v151
	v_ashrrev_i32_e32 v151, 11, v151
	v_add_u32_e32 v151, v151, v152
	v_mad_i32_i24 v152, v151, s82, v150
	v_lshlrev_b32_e32 v153, 12, v151
	v_add3_u32 v153, v152, v153, s62
	v_lshl_add_u32 v154, v151, 8, v152
	v_cmp_gt_i32_e32 vcc, s33, v152
	v_mov_b32_e32 v156, s8
	v_mov_b32_e32 v157, s9
	v_mov_b32_e32 v158, s14
	v_mov_b32_e32 v159, s15
	v_cndmask_b32_e32 v154, v153, v154, vcc
	v_cndmask_b32_e32 v156, v156, v158, vcc
	v_cndmask_b32_e32 v157, v157, v159, vcc
	v_ashrrev_i32_e32 v155, 31, v154
	v_lshlrev_b64 v[154:155], 12, v[154:155]
	v_lshl_add_u64 v[154:155], v[156:157], 0, v[154:155]
	v_lshlrev_b32_e32 v152, 2, v18
	v_mov_b32_e32 v153, 0
	v_lshl_add_u64 v[154:155], v[154:155], 0, v[152:153]
	global_load_dwordx4 v[160:163], v[154:155], off
	global_load_dwordx4 v[164:167], v[154:155], off offset:1024
	global_load_dwordx4 v[168:171], v[154:155], off offset:2048
	global_load_dwordx4 v[172:175], v[154:155], off offset:3072
	s_waitcnt vmcnt(0)
	s_branch .LBB0_1730
.LBB0_1729:
	s_or_b64 exec, exec, s[6:7]
	v_pk_mul_f32 v[58:59], v[14:15], v[14:15]
	v_pk_mul_f32 v[60:61], v[10:11], v[10:11]
	v_pk_mul_f32 v[54:55], v[16:17], v[16:17]
	v_pk_mul_f32 v[56:57], v[12:13], v[12:13]
	v_mov_b32_e32 v62, v58
	v_mov_b32_e32 v63, v60
	v_mov_b32_e32 v60, v59
	v_pk_add_f32 v[58:59], v[62:63], v[60:61]
	v_mov_b32_e32 v60, v54
	v_mov_b32_e32 v61, v56
	v_pk_mul_f32 v[50:51], v[2:3], v[2:3]
	v_pk_mul_f32 v[52:53], v[6:7], v[6:7]
	v_pk_add_f32 v[58:59], v[60:61], v[58:59]
	v_mov_b32_e32 v56, v55
	v_lshl_add_u64 v[46:47], s[16:17], 0, v[42:43]
	v_pk_mul_f32 v[42:43], v[4:5], v[4:5]
	v_pk_mul_f32 v[48:49], v[8:9], v[8:9]
	v_pk_add_f32 v[54:55], v[56:57], v[58:59]
	v_mov_b32_e32 v56, v50
	v_mov_b32_e32 v57, v52
	v_mov_b32_e32 v52, v51
	v_lshl_add_u64 v[44:45], v[46:47], 0, s[40:41]
	v_pk_add_f32 v[50:51], v[56:57], v[52:53]
	v_mov_b32_e32 v52, v42
	v_mov_b32_e32 v53, v48
	v_pk_add_f32 v[50:51], v[52:53], v[50:51]
	v_mov_b32_e32 v48, v43
	v_lshl_add_u64 v[52:53], v[44:45], 0, v[0:1]
	v_pk_add_f32 v[42:43], v[48:49], v[50:51]
	v_add_f32_e32 v37, v54, v55
	global_load_dwordx4 v[48:51], v[20:21], off
	v_lshl_add_u64 v[46:47], v[46:47], 0, v[0:1]
	v_mov_b64_e32 v[148:149], v[52:53]
	global_load_dwordx4 v[52:55], v[52:53], off
	v_add_f32_e32 v37, v43, v37
	global_load_dwordx4 v[56:59], v[46:47], off
	global_load_dwordx4 v[100:103], v[20:21], off offset:1024
	global_load_dwordx4 v[104:107], v[148:149], off offset:1024
	global_load_dwordx4 v[108:111], v[46:47], off offset:1024
	global_load_dwordx4 v[112:115], v[20:21], off offset:2048
	global_load_dwordx4 v[116:119], v[148:149], off offset:2048
	global_load_dwordx4 v[120:123], v[46:47], off offset:2048
	global_load_dwordx4 v[124:127], v[20:21], off offset:3072
	global_load_dwordx4 v[128:131], v[148:149], off offset:3072
	global_load_dwordx4 v[132:135], v[46:47], off offset:3072
	v_add_u32_e32 v150, 0x800, v19
	v_min_i32_e32 v150, 0x43ff, v150
	v_mul_hi_i32 v151, v150, s89
	v_lshrrev_b32_e32 v152, 31, v151
	v_ashrrev_i32_e32 v151, 11, v151
	v_add_u32_e32 v151, v151, v152
	v_mad_i32_i24 v152, v151, s82, v150
	v_lshlrev_b32_e32 v153, 12, v151
	v_add3_u32 v153, v152, v153, s62
	v_lshl_add_u32 v154, v151, 8, v152
	v_cmp_gt_i32_e32 vcc, s33, v152
	v_mov_b32_e32 v156, s8
	v_mov_b32_e32 v157, s9
	v_mov_b32_e32 v158, s14
	v_mov_b32_e32 v159, s15
	v_cndmask_b32_e32 v154, v153, v154, vcc
	v_cndmask_b32_e32 v156, v156, v158, vcc
	v_cndmask_b32_e32 v157, v157, v159, vcc
; __device__ __forceinline__ void phase_prenorm(const int wvs, const Params& p, int layer, int which  , const float* lat, const float* ctx, bool fold) {
;     ...
; #pragma unroll
;     for (int i = 0; i < 4; ++i) ss += v[i][0] * v[i][0] + v[i][1] * v[i][1] + v[i][2] * v[i][2] + v[i][3] * v[i][3];
;     ss = wave_sum(ss); const float rs = rsqrtf(ss * (1.0f / DM) + 1e-6f);
; #pragma unroll
;     for (int i = 0; i < 4; ++i) { const int k = lane * 4 + 256 * i; const f32x4 g4 = *(const f32x4*)(gain + k), s4 = *(const f32x4*)(sc + k), h4v = *(const f32x4*)(sh + k); h4 o;
; #pragma unroll
;       for (int j = 0; j < 4; ++j) o[j] = (hf)((v[i][j] * rs * g4[j]) * (1.0f + s4[j]) + h4v[j]);
;       *(h4*)(A + (size_t)tok * DM + k) = o; }
	v_ashrrev_i32_e32 v155, 31, v154
	v_lshlrev_b64 v[154:155], 12, v[154:155]
	v_lshl_add_u64 v[154:155], v[156:157], 0, v[154:155]
	v_lshlrev_b32_e32 v152, 2, v18
	v_mov_b32_e32 v153, 0
	v_lshl_add_u64 v[154:155], v[154:155], 0, v[152:153]
	global_load_dwordx4 v[160:163], v[154:155], off
	global_load_dwordx4 v[164:167], v[154:155], off offset:1024
	global_load_dwordx4 v[168:171], v[154:155], off offset:2048
	global_load_dwordx4 v[172:175], v[154:155], off offset:3072
	v_add_f32_e32 v37, v42, v37
	v_mov_b32_e32 v41, v1
	v_add_u32_e32 v0, 0x800, v19
	v_add_f32_dpp v37, v37, v37 quad_perm:[1,0,3,2] row_mask:0xf bank_mask:0xf bound_ctrl:1
	s_nop 1
	v_add_f32_dpp v37, v37, v37 quad_perm:[2,3,0,1] row_mask:0xf bank_mask:0xf bound_ctrl:1
	s_nop 1
	v_add_f32_dpp v37, v37, v37 row_half_mirror row_mask:0xf bank_mask:0xf bound_ctrl:1
	s_nop 1
	v_add_f32_dpp v37, v37, v37 row_mirror row_mask:0xf bank_mask:0xf bound_ctrl:1
	s_nop 0
	v_readlane_b32 s4, v37, 16
	v_readlane_b32 s5, v37, 48
	v_readlane_b32 s2, v37, 0
	v_readlane_b32 s3, v37, 32
	v_mov_b32_e32 v42, s4
	v_mov_b32_e32 v43, s5
	v_pk_add_f32 v[42:43], s[2:3], v[42:43]
	s_mov_b64 s[2:3], 0x400000
	v_add_f32_e32 v37, v42, v43
	v_fmamk_f32 v37, v37, 0x3a800000, v205
	v_cmp_gt_f32_e32 vcc, s34, v37
	v_mul_f32_e32 v39, 0x4b800000, v37
	s_nop 0
	v_cndmask_b32_e32 v37, v37, v39, vcc
	v_rsq_f32_e32 v37, v37
	s_nop 0
	v_mul_f32_e32 v39, 0x45800000, v37
	v_cndmask_b32_e32 v42, v37, v39, vcc
	v_pk_mul_f32 v[14:15], v[14:15], v[42:43] op_sel_hi:[1,0]
	v_pk_mul_f32 v[16:17], v[16:17], v[42:43] op_sel_hi:[1,0]
	v_mov_b32_e32 v37, v1
	v_pk_mul_f32 v[10:11], v[10:11], v[42:43] op_sel_hi:[1,0]
	v_pk_mul_f32 v[12:13], v[12:13], v[42:43] op_sel_hi:[1,0]
	v_mov_b32_e32 v39, v1
	v_pk_mul_f32 v[6:7], v[6:7], v[42:43] op_sel_hi:[1,0]
	v_pk_mul_f32 v[8:9], v[8:9], v[42:43] op_sel_hi:[1,0]
	v_pk_mul_f32 v[2:3], v[2:3], v[42:43] op_sel_hi:[1,0]
	v_pk_mul_f32 v[4:5], v[4:5], v[42:43] op_sel_hi:[1,0]
	v_cmp_lt_i32_e32 vcc, s83, v19
	s_or_b64 s[10:11], vcc, s[10:11]
	v_mov_b32_e32 v19, v0
	s_waitcnt vmcnt(15)
	v_pk_mul_f32 v[14:15], v[48:49], v[14:15]
	v_pk_mul_f32 v[16:17], v[50:51], v[16:17]
	s_waitcnt vmcnt(14)
	v_pk_add_f32 v[48:49], v[52:53], 1.0 op_sel_hi:[1,0]
	s_waitcnt vmcnt(13)
	v_pk_fma_f32 v[14:15], v[48:49], v[14:15], v[56:57]
	v_pk_add_f32 v[48:49], v[54:55], 1.0 op_sel_hi:[1,0]
	v_cvt_pk_f16_f32 v14, v14, v15
	v_pk_fma_f32 v[16:17], v[48:49], v[16:17], v[58:59]
	v_lshl_add_u64 v[48:49], v[44:45], 0, v[36:37]
	v_cvt_pk_f16_f32 v15, v16, v17
	global_store_dwordx2 v[34:35], v[14:15], off offset:-1024
	s_waitcnt vmcnt(5)
	v_mov_b64_e32 v[14:15], v[100:101]
	v_mov_b64_e32 v[16:17], v[102:103]
	s_nop 0
	v_mov_b64_e32 v[48:49], v[104:105]
	v_mov_b64_e32 v[50:51], v[106:107]
	s_nop 0
	v_mov_b64_e32 v[52:53], v[108:109]
	v_mov_b64_e32 v[54:55], v[110:111]
	v_pk_mul_f32 v[10:11], v[14:15], v[10:11]
	v_pk_add_f32 v[14:15], v[48:49], 1.0 op_sel_hi:[1,0]
	v_pk_mul_f32 v[12:13], v[16:17], v[12:13]
	v_pk_fma_f32 v[10:11], v[14:15], v[10:11], v[52:53]
	v_pk_add_f32 v[14:15], v[50:51], 1.0 op_sel_hi:[1,0]
	v_cvt_pk_f16_f32 v10, v10, v11
	v_pk_fma_f32 v[12:13], v[14:15], v[12:13], v[54:55]
	v_lshl_add_u64 v[14:15], v[44:45], 0, v[38:39]
	v_cvt_pk_f16_f32 v11, v12, v13
	global_store_dwordx2 v[34:35], v[10:11], off offset:-512
	v_mov_b64_e32 v[10:11], v[112:113]
	v_mov_b64_e32 v[12:13], v[114:115]
	s_nop 0
	v_mov_b64_e32 v[14:15], v[116:117]
	v_mov_b64_e32 v[16:17], v[118:119]
	s_nop 0
	v_mov_b64_e32 v[48:49], v[120:121]
	v_mov_b64_e32 v[50:51], v[122:123]
	v_pk_mul_f32 v[6:7], v[10:11], v[6:7]
	v_pk_add_f32 v[10:11], v[14:15], 1.0 op_sel_hi:[1,0]
	v_pk_mul_f32 v[8:9], v[12:13], v[8:9]
	v_pk_fma_f32 v[6:7], v[10:11], v[6:7], v[48:49]
	v_pk_add_f32 v[10:11], v[16:17], 1.0 op_sel_hi:[1,0]
	v_cvt_pk_f16_f32 v6, v6, v7
	v_pk_fma_f32 v[8:9], v[10:11], v[8:9], v[50:51]
	v_lshl_add_u64 v[10:11], v[44:45], 0, v[40:41]
	v_cvt_pk_f16_f32 v7, v8, v9
	global_store_dwordx2 v[34:35], v[6:7], off
	v_mov_b64_e32 v[6:7], v[124:125]
	v_mov_b64_e32 v[8:9], v[126:127]
	s_nop 0
	v_mov_b64_e32 v[10:11], v[128:129]
	v_mov_b64_e32 v[12:13], v[130:131]
	s_nop 0
	v_mov_b64_e32 v[14:15], v[132:133]
	v_mov_b64_e32 v[16:17], v[134:135]
	v_pk_mul_f32 v[2:3], v[2:3], v[6:7]
	v_pk_add_f32 v[6:7], v[10:11], 1.0 op_sel_hi:[1,0]
	v_pk_mul_f32 v[4:5], v[4:5], v[8:9]
	v_pk_fma_f32 v[2:3], v[2:3], v[6:7], v[14:15]
	v_pk_add_f32 v[6:7], v[12:13], 1.0 op_sel_hi:[1,0]
	v_cvt_pk_f16_f32 v2, v2, v3
	v_pk_fma_f32 v[4:5], v[4:5], v[6:7], v[16:17]
	s_nop 0
	v_cvt_pk_f16_f32 v3, v4, v5
	global_store_dwordx2 v[34:35], v[2:3], off offset:512
	v_lshl_add_u64 v[34:35], v[34:35], 0, s[2:3]
	s_andn2_b64 exec, exec, s[10:11]
	s_cbranch_execz .LBB0_1738
; __device__ __forceinline__ void phase_prenorm(const int wvs, const Params& p, int layer, int which  , const float* lat, const float* ctx, bool fold) {
;     ...
;   for (int tok = gw; tok < NTOK; tok += NWAVES) {
;     bool isctx; const size_t ro = xrow_off(tok, isctx); const float* xr = (isctx ? ctx : lat) + ro; const int mi = mod_index(tok);
;     const float* sh = mods + (size_t)mi * 6144 + (which == 0 ? 0 : 3) * DM; const float* sc = sh + DM;
;     f32x4 v[4]; float ss = 0.f;
; #pragma unroll
;     for (int i = 0; i < 4; ++i) v[i] = *(const f32x4*)(xr + lane * 4 + 256 * i);
;     if (fold && isctx) {
;       const float* gt = (const float*)(p.ws + OFF_MODS) + (size_t)4 * 6144 + (which == 1 ? 2 : 5) * DM;
;       const float* part = (const float*)(p.ws + OFF_RI) + ro; float* xc = (float*)(p.ws + OFF_XCTX) + ro;
; #pragma unroll
;       for (int i = 0; i < 4; ++i) { const int k = lane * 4 + 256 * i; f32x4 s = *(const f32x4*)(part + k);
; #pragma unroll
;         for (int q = 1; q < 4; ++q) s += *(const f32x4*)(part + (size_t)q * (NB * LCTX * DM) + k);
;         v[i] += *(const f32x4*)(gt + k) * s; *(f32x4*)(xc + k) = v[i]; } }
.LBB0_1730:
	v_mul_hi_i32 v0, v19, s89
	v_lshrrev_b32_e32 v2, 31, v0
	v_ashrrev_i32_e32 v0, 11, v0
	v_add_u32_e32 v0, v0, v2
	v_mad_i32_i24 v4, v0, s82, v19
	v_cmp_gt_i32_e32 vcc, s33, v4
	v_cmp_lt_i32_e64 s[6:7], s29, v4
	s_and_saveexec_b64 s[2:3], s[6:7]
	s_xor_b64 s[6:7], exec, s[2:3]
	v_lshlrev_b32_e32 v2, 12, v0
	v_add3_u32 v44, v4, v2, s62
	v_mul_hi_i32_i24_e32 v43, 0x6000, v0
	v_mul_i32_i24_e32 v42, 0x6000, v0
	s_or_saveexec_b64 s[6:7], s[6:7]
	v_mov_b64_e32 v[2:3], s[8:9]
	s_xor_b64 exec, exec, s[6:7]
	v_lshl_add_u32 v44, v0, 8, v4
	v_mov_b64_e32 v[42:43], 0x18000
	v_mov_b64_e32 v[2:3], s[14:15]
	s_or_b64 exec, exec, s[6:7]
	v_ashrrev_i32_e32 v45, 31, v44
	v_lshlrev_b64 v[4:5], 12, v[44:45]
	v_lshl_add_u64 v[2:3], v[2:3], 0, v[4:5]
	v_lshlrev_b32_e32 v0, 2, v18
	v_lshl_add_u64 v[2:3], v[2:3], 0, v[0:1]
	s_waitcnt vmcnt(4)
	v_mov_b64_e32 v[14:15], v[160:161]
	v_mov_b64_e32 v[16:17], v[162:163]
	v_mov_b64_e32 v[10:11], v[164:165]
	v_mov_b64_e32 v[12:13], v[166:167]
	v_mov_b64_e32 v[6:7], v[168:169]
	v_mov_b64_e32 v[8:9], v[170:171]
	v_mov_b64_e32 v[2:3], v[172:173]
	v_mov_b64_e32 v[4:5], v[174:175]
	s_and_b64 s[2:3], s[38:39], vcc
	s_xor_b64 s[2:3], s[2:3], -1
	s_and_saveexec_b64 s[4:5], s[2:3]
	s_xor_b64 s[6:7], exec, s[4:5]
	s_andn2_saveexec_b64 s[6:7], s[6:7]
	s_cbranch_execz .LBB0_1729
	v_lshlrev_b64 v[44:45], 10, v[44:45]
	v_lshlrev_b64 v[58:59], 2, v[44:45]
	v_lshl_add_u64 v[50:51], v[30:31], 0, v[58:59]
	v_add_co_u32_e32 v52, vcc, 0x400000, v50
	global_load_dwordx4 v[44:47], v[50:51], off
	s_nop 0
	v_addc_co_u32_e32 v53, vcc, 0, v51, vcc
	global_load_dwordx4 v[54:57], v[52:53], off
	v_add_co_u32_e32 v48, vcc, 0x800000, v50
	s_waitcnt vmcnt(0)
	v_pk_add_f32 v[56:57], v[46:47], v[56:57]
	v_addc_co_u32_e32 v49, vcc, 0, v51, vcc
	v_pk_add_f32 v[54:55], v[44:45], v[54:55]
	global_load_dwordx4 v[44:47], v[48:49], off
	s_waitcnt vmcnt(0)
	v_pk_add_f32 v[60:61], v[56:57], v[46:47]
	v_add_co_u32_e32 v46, vcc, 0xc00000, v50
	v_pk_add_f32 v[44:45], v[54:55], v[44:45]
	s_nop 0
	v_addc_co_u32_e32 v47, vcc, 0, v51, vcc
	global_load_dwordx4 v[54:57], v[46:47], off
	s_waitcnt vmcnt(0)
	v_pk_add_f32 v[60:61], v[60:61], v[56:57]
	v_pk_add_f32 v[44:45], v[44:45], v[54:55]
	global_load_dwordx4 v[54:57], v[22:23], off
	s_waitcnt vmcnt(0)
	v_pk_fma_f32 v[16:17], v[60:61], v[56:57], v[16:17]
	v_pk_fma_f32 v[14:15], v[44:45], v[54:55], v[14:15]
	v_lshl_add_u64 v[44:45], v[32:33], 0, v[58:59]
	global_store_dwordx4 v[44:45], v[14:17], off
	global_load_dwordx4 v[54:57], v[50:51], off offset:1024
	global_load_dwordx4 v[58:61], v[52:53], off offset:1024
	s_waitcnt vmcnt(0)
	v_pk_add_f32 v[60:61], v[56:57], v[60:61]
	v_pk_add_f32 v[58:59], v[54:55], v[58:59]
	global_load_dwordx4 v[54:57], v[48:49], off offset:1024
	s_waitcnt vmcnt(0)
	v_pk_add_f32 v[60:61], v[60:61], v[56:57]
	v_pk_add_f32 v[58:59], v[58:59], v[54:55]
	global_load_dwordx4 v[54:57], v[46:47], off offset:1024
	s_waitcnt vmcnt(0)
	v_pk_add_f32 v[60:61], v[60:61], v[56:57]
	v_pk_add_f32 v[58:59], v[58:59], v[54:55]
	global_load_dwordx4 v[54:57], v[24:25], off
	s_waitcnt vmcnt(0)
	v_pk_fma_f32 v[12:13], v[60:61], v[56:57], v[12:13]
	v_pk_fma_f32 v[10:11], v[58:59], v[54:55], v[10:11]
	global_store_dwordx4 v[44:45], v[10:13], off offset:1024
	global_load_dwordx4 v[54:57], v[50:51], off offset:2048
	global_load_dwordx4 v[58:61], v[52:53], off offset:2048
	s_waitcnt vmcnt(0)
	v_pk_add_f32 v[60:61], v[56:57], v[60:61]
	v_pk_add_f32 v[58:59], v[54:55], v[58:59]
	global_load_dwordx4 v[54:57], v[48:49], off offset:2048
	s_waitcnt vmcnt(0)
	v_pk_add_f32 v[60:61], v[60:61], v[56:57]
	v_pk_add_f32 v[58:59], v[58:59], v[54:55]
	global_load_dwordx4 v[54:57], v[46:47], off offset:2048
	s_waitcnt vmcnt(0)
	v_pk_add_f32 v[60:61], v[60:61], v[56:57]
	v_pk_add_f32 v[58:59], v[58:59], v[54:55]
	global_load_dwordx4 v[54:57], v[26:27], off
	s_waitcnt vmcnt(0)
	v_pk_fma_f32 v[8:9], v[60:61], v[56:57], v[8:9]
	v_pk_fma_f32 v[6:7], v[58:59], v[54:55], v[6:7]
	global_store_dwordx4 v[44:45], v[6:9], off offset:2048
	global_load_dwordx4 v[54:57], v[50:51], off offset:3072
	s_nop 0
	global_load_dwordx4 v[50:53], v[52:53], off offset:3072
	s_waitcnt vmcnt(0)
	v_pk_add_f32 v[54:55], v[54:55], v[50:51]
	global_load_dwordx4 v[48:51], v[48:49], off offset:3072
	v_pk_add_f32 v[52:53], v[56:57], v[52:53]
	s_waitcnt vmcnt(0)
	v_pk_add_f32 v[50:51], v[52:53], v[50:51]
	v_pk_add_f32 v[52:53], v[54:55], v[48:49]
	global_load_dwordx4 v[46:49], v[46:47], off offset:3072
	s_waitcnt vmcnt(0)
	v_pk_add_f32 v[50:51], v[50:51], v[48:49]
	v_pk_add_f32 v[52:53], v[52:53], v[46:47]
	global_load_dwordx4 v[46:49], v[28:29], off
	s_waitcnt vmcnt(0)
	v_pk_fma_f32 v[4:5], v[50:51], v[48:49], v[4:5]
	v_pk_fma_f32 v[2:3], v[52:53], v[46:47], v[2:3]
	global_store_dwordx4 v[44:45], v[2:5], off offset:3072
	s_branch .LBB0_1729
